# lane-permuted (ds_bpermute) bf16 row stores in the EpiProj epilogue only
# speedup vs baseline: 1.0040x; 1.0040x over previous
.LBB0_1117:
	v_mbcnt_lo_u32_b32 v238, -1, 0
	v_mbcnt_hi_u32_b32 v238, -1, v238
	v_and_b32_e32 v236, 3, v238
	v_lshrrev_b32_e32 v238, 2, v238
	v_lshl_or_b32 v238, v236, 4, v238
	v_lshlrev_b32_e32 v238, 2, v238
	v_lshl_add_u32 v148, s6, 8, v153
	v_ashrrev_i32_e32 v149, 31, v148
	v_lshl_add_u64 v[146:147], v[148:149], 3, s[16:17]
	global_load_dwordx2 v[150:151], v[146:147], off
	global_load_dwordx2 v[190:191], v[146:147], off offset:128
	global_load_dwordx2 v[192:193], v[146:147], off offset:256
	global_load_dwordx2 v[194:195], v[146:147], off offset:384
	global_load_dwordx2 v[196:197], v[146:147], off offset:1024
	global_load_dwordx2 v[198:199], v[146:147], off offset:1152
	global_load_dwordx2 v[200:201], v[146:147], off offset:1280
	global_load_dwordx2 v[202:203], v[146:147], off offset:1408
	s_cmp_gt_i32 s0, 57
	s_cselect_b64 s[36:37], -1, 0
	s_mov_b64 s[8:9], -1
	s_waitcnt vmcnt(0)
	v_ffbh_u32_e32 v152, v151
	v_min_u32_e32 v152, 32, v152
	v_lshlrev_b64 v[150:151], v152, v[150:151]
	v_min_u32_e32 v150, 1, v150
	v_or_b32_e32 v150, v151, v150
	v_cvt_f32_u32_e32 v150, v150
	v_sub_u32_e32 v151, 32, v152
	v_ldexp_f32 v150, v150, v151
	v_fmamk_f32 v150, v150, 0x2a000000, v159
	v_cmp_gt_f32_e32 vcc, s54, v150
	v_mul_f32_e32 v151, 0x4b800000, v150
	s_nop 0
	v_cndmask_b32_e32 v150, v150, v151, vcc
	v_rsq_f32_e32 v150, v150
	s_nop 0
	v_mul_f32_e32 v151, 0x45800000, v150
	v_cndmask_b32_e32 v152, v150, v151, vcc
	v_cndmask_b32_e64 v150, 0, 1, s[24:25]
	s_and_b64 vcc, exec, s[36:37]
	v_cmp_ne_u32_e64 s[6:7], 1, v150
	s_cbranch_vccz .LBB0_1121
	s_and_b64 vcc, exec, s[6:7]
	s_cbranch_vccnz .LBB0_1120
	v_lshlrev_b64 v[150:151], 8, v[148:149]
	v_lshl_add_u64 v[150:151], v[136:137], 0, v[150:151]
	v_pk_mul_f32 v[162:163], v[126:127], v[152:153] op_sel_hi:[1,0]
	v_pk_mul_f32 v[160:161], v[124:125], v[152:153] op_sel_hi:[1,0]
	global_store_dwordx4 v[150:151], v[160:163], off
	s_nop 1
	v_pk_mul_f32 v[162:163], v[122:123], v[152:153] op_sel_hi:[1,0]
	v_pk_mul_f32 v[160:161], v[120:121], v[152:153] op_sel_hi:[1,0]
	global_store_dwordx4 v[150:151], v[160:163], off offset:16

.LBB0_1121:
	v_lshl_or_b32 v150, s0, 8, v155
	s_andn2_b64 vcc, exec, s[8:9]
	v_ashrrev_i32_e32 v151, 31, v150
	s_cbranch_vccnz .LBB0_1123
	v_readlane_b32 s0, v233, 17
	v_pk_mul_f32 v[124:125], v[124:125], v[152:153] op_sel_hi:[1,0]
	v_readlane_b32 s1, v233, 18
	v_pk_mul_f32 v[160:161], v[122:123], v[152:153] op_sel_hi:[1,0]
	v_pk_mul_f32 v[122:123], v[120:121], v[152:153] op_sel_hi:[1,0]
	v_cvt_pk_bf16_f32 v120, v124, v125
	v_mov_b64_e32 v[124:125], s[0:1]
	v_pk_mul_f32 v[126:127], v[126:127], v[152:153] op_sel_hi:[1,0]
	v_mad_i64_i32 v[124:125], s[0:1], v148, s55, v[124:125]
	v_cvt_pk_bf16_f32 v121, v126, v127
	v_cvt_pk_bf16_f32 v122, v122, v123
	v_cvt_pk_bf16_f32 v123, v160, v161
	v_lshl_add_u64 v[124:125], v[150:151], 1, v[124:125]
	ds_bpermute_b32 v236, v238, v124
	ds_bpermute_b32 v237, v238, v125
	ds_bpermute_b32 v120, v238, v120
	ds_bpermute_b32 v121, v238, v121
	ds_bpermute_b32 v122, v238, v122
	ds_bpermute_b32 v123, v238, v123
	s_waitcnt lgkmcnt(0)
	global_store_dwordx4 v[236:237], v[120:123], off
	v_pk_mul_f32 v[118:119], v[118:119], v[152:153] op_sel_hi:[1,0]
	v_pk_mul_f32 v[116:117], v[116:117], v[152:153] op_sel_hi:[1,0]
	v_pk_mul_f32 v[120:121], v[114:115], v[152:153] op_sel_hi:[1,0]
	v_pk_mul_f32 v[114:115], v[112:113], v[152:153] op_sel_hi:[1,0]
	v_cvt_pk_bf16_f32 v112, v116, v117
	v_cvt_pk_bf16_f32 v113, v118, v119
	v_cvt_pk_bf16_f32 v114, v114, v115
	v_cvt_pk_bf16_f32 v115, v120, v121
	ds_bpermute_b32 v112, v238, v112
	ds_bpermute_b32 v113, v238, v113
	ds_bpermute_b32 v114, v238, v114
	ds_bpermute_b32 v115, v238, v115
	s_waitcnt lgkmcnt(0)
	global_store_dwordx4 v[236:237], v[112:115], off offset:256

.LBB0_1127:
	s_andn2_b64 vcc, exec, s[0:1]
	s_cbranch_vccnz .LBB0_1129
	v_readlane_b32 s0, v233, 17
	v_pk_mul_f32 v[108:109], v[108:109], v[114:115] op_sel_hi:[1,0]
	v_readlane_b32 s1, v233, 18
	v_pk_mul_f32 v[116:117], v[106:107], v[114:115] op_sel_hi:[1,0]
	v_pk_mul_f32 v[106:107], v[104:105], v[114:115] op_sel_hi:[1,0]
	v_cvt_pk_bf16_f32 v104, v108, v109
	v_mov_b64_e32 v[108:109], s[0:1]
	v_pk_mul_f32 v[110:111], v[110:111], v[114:115] op_sel_hi:[1,0]
	v_mad_i64_i32 v[108:109], s[0:1], v112, s55, v[108:109]
	v_cvt_pk_bf16_f32 v105, v110, v111
	v_cvt_pk_bf16_f32 v106, v106, v107
	v_cvt_pk_bf16_f32 v107, v116, v117
	v_lshl_add_u64 v[108:109], v[150:151], 1, v[108:109]
	ds_bpermute_b32 v236, v238, v108
	ds_bpermute_b32 v237, v238, v109
	ds_bpermute_b32 v104, v238, v104
	ds_bpermute_b32 v105, v238, v105
	ds_bpermute_b32 v106, v238, v106
	ds_bpermute_b32 v107, v238, v107
	s_waitcnt lgkmcnt(0)
	global_store_dwordx4 v[236:237], v[104:107], off
	v_pk_mul_f32 v[102:103], v[102:103], v[114:115] op_sel_hi:[1,0]
	v_pk_mul_f32 v[100:101], v[100:101], v[114:115] op_sel_hi:[1,0]
	v_pk_mul_f32 v[104:105], v[98:99], v[114:115] op_sel_hi:[1,0]
	v_pk_mul_f32 v[98:99], v[96:97], v[114:115] op_sel_hi:[1,0]
	v_cvt_pk_bf16_f32 v96, v100, v101
	v_cvt_pk_bf16_f32 v97, v102, v103
	v_cvt_pk_bf16_f32 v98, v98, v99
	v_cvt_pk_bf16_f32 v99, v104, v105
	ds_bpermute_b32 v96, v238, v96
	ds_bpermute_b32 v97, v238, v97
	ds_bpermute_b32 v98, v238, v98
	ds_bpermute_b32 v99, v238, v99
	s_waitcnt lgkmcnt(0)
	global_store_dwordx4 v[236:237], v[96:99], off offset:256

.LBB0_1133:
	s_andn2_b64 vcc, exec, s[0:1]
	s_cbranch_vccnz .LBB0_1135
	v_readlane_b32 s0, v233, 17
	v_pk_mul_f32 v[92:93], v[92:93], v[98:99] op_sel_hi:[1,0]
	v_readlane_b32 s1, v233, 18
	v_pk_mul_f32 v[100:101], v[90:91], v[98:99] op_sel_hi:[1,0]
	v_pk_mul_f32 v[90:91], v[88:89], v[98:99] op_sel_hi:[1,0]
	v_cvt_pk_bf16_f32 v88, v92, v93
	v_mov_b64_e32 v[92:93], s[0:1]
	v_pk_mul_f32 v[94:95], v[94:95], v[98:99] op_sel_hi:[1,0]
	v_mad_i64_i32 v[92:93], s[0:1], v96, s55, v[92:93]
	v_cvt_pk_bf16_f32 v89, v94, v95
	v_cvt_pk_bf16_f32 v90, v90, v91
	v_cvt_pk_bf16_f32 v91, v100, v101
	v_lshl_add_u64 v[92:93], v[150:151], 1, v[92:93]
	ds_bpermute_b32 v236, v238, v92
	ds_bpermute_b32 v237, v238, v93
	ds_bpermute_b32 v88, v238, v88
	ds_bpermute_b32 v89, v238, v89
	ds_bpermute_b32 v90, v238, v90
	ds_bpermute_b32 v91, v238, v91
	s_waitcnt lgkmcnt(0)
	global_store_dwordx4 v[236:237], v[88:91], off
	v_pk_mul_f32 v[86:87], v[86:87], v[98:99] op_sel_hi:[1,0]
	v_pk_mul_f32 v[84:85], v[84:85], v[98:99] op_sel_hi:[1,0]
	v_pk_mul_f32 v[88:89], v[82:83], v[98:99] op_sel_hi:[1,0]
	v_pk_mul_f32 v[82:83], v[80:81], v[98:99] op_sel_hi:[1,0]
	v_cvt_pk_bf16_f32 v80, v84, v85
	v_cvt_pk_bf16_f32 v81, v86, v87
	v_cvt_pk_bf16_f32 v82, v82, v83
	v_cvt_pk_bf16_f32 v83, v88, v89
	ds_bpermute_b32 v80, v238, v80
	ds_bpermute_b32 v81, v238, v81
	ds_bpermute_b32 v82, v238, v82
	ds_bpermute_b32 v83, v238, v83
	s_waitcnt lgkmcnt(0)
	global_store_dwordx4 v[236:237], v[80:83], off offset:256

.LBB0_1139:
	s_andn2_b64 vcc, exec, s[0:1]
	s_cbranch_vccnz .LBB0_1141
	v_readlane_b32 s0, v233, 17
	v_pk_mul_f32 v[76:77], v[76:77], v[82:83] op_sel_hi:[1,0]
	v_readlane_b32 s1, v233, 18
	v_pk_mul_f32 v[84:85], v[74:75], v[82:83] op_sel_hi:[1,0]
	v_pk_mul_f32 v[74:75], v[72:73], v[82:83] op_sel_hi:[1,0]
	v_cvt_pk_bf16_f32 v72, v76, v77
	v_mov_b64_e32 v[76:77], s[0:1]
	v_pk_mul_f32 v[78:79], v[78:79], v[82:83] op_sel_hi:[1,0]
	v_mad_i64_i32 v[76:77], s[0:1], v80, s55, v[76:77]
	v_cvt_pk_bf16_f32 v73, v78, v79
	v_cvt_pk_bf16_f32 v74, v74, v75
	v_cvt_pk_bf16_f32 v75, v84, v85
	v_lshl_add_u64 v[76:77], v[150:151], 1, v[76:77]
	ds_bpermute_b32 v236, v238, v76
	ds_bpermute_b32 v237, v238, v77
	ds_bpermute_b32 v72, v238, v72
	ds_bpermute_b32 v73, v238, v73
	ds_bpermute_b32 v74, v238, v74
	ds_bpermute_b32 v75, v238, v75
	s_waitcnt lgkmcnt(0)
	global_store_dwordx4 v[236:237], v[72:75], off
	v_pk_mul_f32 v[70:71], v[70:71], v[82:83] op_sel_hi:[1,0]
	v_pk_mul_f32 v[68:69], v[68:69], v[82:83] op_sel_hi:[1,0]
	v_pk_mul_f32 v[72:73], v[66:67], v[82:83] op_sel_hi:[1,0]
	v_pk_mul_f32 v[66:67], v[64:65], v[82:83] op_sel_hi:[1,0]
	v_cvt_pk_bf16_f32 v64, v68, v69
	v_cvt_pk_bf16_f32 v65, v70, v71
	v_cvt_pk_bf16_f32 v66, v66, v67
	v_cvt_pk_bf16_f32 v67, v72, v73
	ds_bpermute_b32 v64, v238, v64
	ds_bpermute_b32 v65, v238, v65
	ds_bpermute_b32 v66, v238, v66
	ds_bpermute_b32 v67, v238, v67
	s_waitcnt lgkmcnt(0)
	global_store_dwordx4 v[236:237], v[64:67], off offset:256

.LBB0_1145:
	s_andn2_b64 vcc, exec, s[0:1]
	s_cbranch_vccnz .LBB0_1147
	v_readlane_b32 s0, v233, 17
	v_pk_mul_f32 v[60:61], v[60:61], v[64:65] op_sel_hi:[1,0]
	v_readlane_b32 s1, v233, 18
	v_pk_mul_f32 v[68:69], v[58:59], v[64:65] op_sel_hi:[1,0]
	v_pk_mul_f32 v[58:59], v[56:57], v[64:65] op_sel_hi:[1,0]
	v_cvt_pk_bf16_f32 v56, v60, v61
	v_mov_b64_e32 v[60:61], s[0:1]
	v_pk_mul_f32 v[62:63], v[62:63], v[64:65] op_sel_hi:[1,0]
	v_mad_i64_i32 v[60:61], s[0:1], v66, s55, v[60:61]
	v_cvt_pk_bf16_f32 v57, v62, v63
	v_cvt_pk_bf16_f32 v58, v58, v59
	v_cvt_pk_bf16_f32 v59, v68, v69
	v_lshl_add_u64 v[60:61], v[150:151], 1, v[60:61]
	ds_bpermute_b32 v236, v238, v60
	ds_bpermute_b32 v237, v238, v61
	ds_bpermute_b32 v56, v238, v56
	ds_bpermute_b32 v57, v238, v57
	ds_bpermute_b32 v58, v238, v58
	ds_bpermute_b32 v59, v238, v59
	s_waitcnt lgkmcnt(0)
	global_store_dwordx4 v[236:237], v[56:59], off
	v_pk_mul_f32 v[54:55], v[54:55], v[64:65] op_sel_hi:[1,0]
	v_pk_mul_f32 v[52:53], v[52:53], v[64:65] op_sel_hi:[1,0]
	v_pk_mul_f32 v[56:57], v[50:51], v[64:65] op_sel_hi:[1,0]
	v_pk_mul_f32 v[50:51], v[48:49], v[64:65] op_sel_hi:[1,0]
	v_cvt_pk_bf16_f32 v48, v52, v53
	v_cvt_pk_bf16_f32 v49, v54, v55
	v_cvt_pk_bf16_f32 v50, v50, v51
	v_cvt_pk_bf16_f32 v51, v56, v57
	ds_bpermute_b32 v48, v238, v48
	ds_bpermute_b32 v49, v238, v49
	ds_bpermute_b32 v50, v238, v50
	ds_bpermute_b32 v51, v238, v51
	s_waitcnt lgkmcnt(0)
	global_store_dwordx4 v[236:237], v[48:51], off offset:256

.LBB0_1151:
	s_andn2_b64 vcc, exec, s[0:1]
	s_cbranch_vccnz .LBB0_1153
	v_readlane_b32 s0, v233, 17
	v_pk_mul_f32 v[44:45], v[44:45], v[48:49] op_sel_hi:[1,0]
	v_readlane_b32 s1, v233, 18
	v_pk_mul_f32 v[52:53], v[42:43], v[48:49] op_sel_hi:[1,0]
	v_pk_mul_f32 v[42:43], v[40:41], v[48:49] op_sel_hi:[1,0]
	v_cvt_pk_bf16_f32 v40, v44, v45
	v_mov_b64_e32 v[44:45], s[0:1]
	v_pk_mul_f32 v[46:47], v[46:47], v[48:49] op_sel_hi:[1,0]
	v_mad_i64_i32 v[44:45], s[0:1], v50, s55, v[44:45]
	v_cvt_pk_bf16_f32 v41, v46, v47
	v_cvt_pk_bf16_f32 v42, v42, v43
	v_cvt_pk_bf16_f32 v43, v52, v53
	v_lshl_add_u64 v[44:45], v[150:151], 1, v[44:45]
	ds_bpermute_b32 v236, v238, v44
	ds_bpermute_b32 v237, v238, v45
	ds_bpermute_b32 v40, v238, v40
	ds_bpermute_b32 v41, v238, v41
	ds_bpermute_b32 v42, v238, v42
	ds_bpermute_b32 v43, v238, v43
	s_waitcnt lgkmcnt(0)
	global_store_dwordx4 v[236:237], v[40:43], off
	v_pk_mul_f32 v[38:39], v[38:39], v[48:49] op_sel_hi:[1,0]
	v_pk_mul_f32 v[36:37], v[36:37], v[48:49] op_sel_hi:[1,0]
	v_pk_mul_f32 v[40:41], v[34:35], v[48:49] op_sel_hi:[1,0]
	v_pk_mul_f32 v[34:35], v[32:33], v[48:49] op_sel_hi:[1,0]
	v_cvt_pk_bf16_f32 v32, v36, v37
	v_cvt_pk_bf16_f32 v33, v38, v39
	v_cvt_pk_bf16_f32 v34, v34, v35
	v_cvt_pk_bf16_f32 v35, v40, v41
	ds_bpermute_b32 v32, v238, v32
	ds_bpermute_b32 v33, v238, v33
	ds_bpermute_b32 v34, v238, v34
	ds_bpermute_b32 v35, v238, v35
	s_waitcnt lgkmcnt(0)
	global_store_dwordx4 v[236:237], v[32:35], off offset:256

.LBB0_1157:
	s_andn2_b64 vcc, exec, s[0:1]
	s_cbranch_vccnz .LBB0_1159
	v_readlane_b32 s0, v233, 17
	v_pk_mul_f32 v[28:29], v[28:29], v[32:33] op_sel_hi:[1,0]
	v_readlane_b32 s1, v233, 18
	v_pk_mul_f32 v[36:37], v[26:27], v[32:33] op_sel_hi:[1,0]
	v_pk_mul_f32 v[26:27], v[24:25], v[32:33] op_sel_hi:[1,0]
	v_cvt_pk_bf16_f32 v24, v28, v29
	v_mov_b64_e32 v[28:29], s[0:1]
	v_pk_mul_f32 v[30:31], v[30:31], v[32:33] op_sel_hi:[1,0]
	v_mad_i64_i32 v[28:29], s[0:1], v34, s55, v[28:29]
	v_cvt_pk_bf16_f32 v25, v30, v31
	v_cvt_pk_bf16_f32 v26, v26, v27
	v_cvt_pk_bf16_f32 v27, v36, v37
	v_lshl_add_u64 v[28:29], v[150:151], 1, v[28:29]
	ds_bpermute_b32 v236, v238, v28
	ds_bpermute_b32 v237, v238, v29
	ds_bpermute_b32 v24, v238, v24
	ds_bpermute_b32 v25, v238, v25
	ds_bpermute_b32 v26, v238, v26
	ds_bpermute_b32 v27, v238, v27
	s_waitcnt lgkmcnt(0)
	global_store_dwordx4 v[236:237], v[24:27], off
	v_pk_mul_f32 v[22:23], v[22:23], v[32:33] op_sel_hi:[1,0]
	v_pk_mul_f32 v[20:21], v[20:21], v[32:33] op_sel_hi:[1,0]
	v_pk_mul_f32 v[24:25], v[18:19], v[32:33] op_sel_hi:[1,0]
	v_pk_mul_f32 v[18:19], v[16:17], v[32:33] op_sel_hi:[1,0]
	v_cvt_pk_bf16_f32 v16, v20, v21
	v_cvt_pk_bf16_f32 v17, v22, v23
	v_cvt_pk_bf16_f32 v18, v18, v19
	v_cvt_pk_bf16_f32 v19, v24, v25
	ds_bpermute_b32 v16, v238, v16
	ds_bpermute_b32 v17, v238, v17
	ds_bpermute_b32 v18, v238, v18
	ds_bpermute_b32 v19, v238, v19
	s_waitcnt lgkmcnt(0)
	global_store_dwordx4 v[236:237], v[16:19], off offset:256

.LBB0_1165:
	v_readlane_b32 s0, v233, 17
	v_pk_mul_f32 v[12:13], v[12:13], v[18:19] op_sel_hi:[1,0]
	v_readlane_b32 s1, v233, 18
	v_pk_mul_f32 v[20:21], v[10:11], v[18:19] op_sel_hi:[1,0]
	v_pk_mul_f32 v[10:11], v[8:9], v[18:19] op_sel_hi:[1,0]
	v_cvt_pk_bf16_f32 v8, v12, v13
	v_mov_b64_e32 v[12:13], s[0:1]
	v_pk_mul_f32 v[14:15], v[14:15], v[18:19] op_sel_hi:[1,0]
	v_mad_i64_i32 v[12:13], s[0:1], v16, s55, v[12:13]
	v_cvt_pk_bf16_f32 v9, v14, v15
	v_cvt_pk_bf16_f32 v10, v10, v11
	v_cvt_pk_bf16_f32 v11, v20, v21
	v_lshl_add_u64 v[12:13], v[150:151], 1, v[12:13]
	ds_bpermute_b32 v236, v238, v12
	ds_bpermute_b32 v237, v238, v13
	ds_bpermute_b32 v8, v238, v8
	ds_bpermute_b32 v9, v238, v9
	ds_bpermute_b32 v10, v238, v10
	ds_bpermute_b32 v11, v238, v11
	s_waitcnt lgkmcnt(0)
	global_store_dwordx4 v[236:237], v[8:11], off
	v_pk_mul_f32 v[6:7], v[6:7], v[18:19] op_sel_hi:[1,0]
	v_pk_mul_f32 v[4:5], v[4:5], v[18:19] op_sel_hi:[1,0]
	v_pk_mul_f32 v[8:9], v[2:3], v[18:19] op_sel_hi:[1,0]
	v_pk_mul_f32 v[2:3], v[0:1], v[18:19] op_sel_hi:[1,0]
	v_cvt_pk_bf16_f32 v0, v4, v5
	v_cvt_pk_bf16_f32 v1, v6, v7
	v_cvt_pk_bf16_f32 v2, v2, v3
	v_cvt_pk_bf16_f32 v3, v8, v9
	ds_bpermute_b32 v0, v238, v0
	ds_bpermute_b32 v1, v238, v1
	ds_bpermute_b32 v2, v238, v2
	ds_bpermute_b32 v3, v238, v3
	s_waitcnt lgkmcnt(0)
	global_store_dwordx4 v[236:237], v[0:3], off offset:256
	s_andn2_b64 vcc, exec, s[4:5]
	s_mov_b64 s[0:1], -1
	s_cbranch_vccnz .LBB0_1106
